# adds prep-phase activation loop with all 16 loads issued up front (8 trips unrolled), on top of previous version
# speedup vs baseline: 1.0205x; 1.0081x over previous
; DI float bf2f(u16 h) { return __uint_as_float(((unsigned)h) << 16); }
; DI float sigmoidf_(float x) { return 1.f / (1.f + __expf(-x)); }
; DI void phase_prep(const PRef& p, int l) {
;     ...
;     for (int idx = tid; idx < 32 * 128; idx += 512) {
;       const int i = idx >> 7, j = idx & 127, tok = tk0 + i, col = 768 + j;
;       float pv = bf2f(rw[(size_t)tok * 896 + col]);
;       float pp = ((tok & (SEQ - 1)) != 0) ? bf2f(rw[(size_t)(tok - 1) * 896 + col]) : 0.f;
;       float ps = pv + (pp - pv) * mu[col];
;       float a = (j < 32) ? tanhf(ps) : (j < 64) ? ps : sigmoidf_(ps);
;       act[i * 128 + j] = a;
.LBB0_1061:
	s_lshl_b32 s19, s18, 5
	s_barrier
	s_and_saveexec_b64 s[2:3], s[6:7]
	s_cbranch_execz .LBB0_1076
	global_load_dword v40, v[18:19], off offset:3072
	v_mov_b32_e32 v41, v16
	v_ashrrev_i32_e32 v42, 7, v76
	v_add_u32_e32 v42, s19, v42
	v_mad_i64_i32 v[46:47], s[14:15], v42, s79, v[32:33]
	global_load_ushort v130, v[46:47], off
	v_and_b32_e32 v45, 0xfff, v42
	v_cmp_ne_u32_e32 vcc, 0, v45
	s_nop 1
	v_cndmask_b32_e64 v150, 0, -1, vcc
	v_add_u32_e32 v45, v42, v150
	v_mad_i64_i32 v[46:47], s[14:15], v45, s79, v[32:33]
	global_load_ushort v131, v[46:47], off
	v_add_u32_e32 v49, 4, v42
	v_mad_i64_i32 v[46:47], s[14:15], v49, s79, v[32:33]
	global_load_ushort v132, v[46:47], off
	v_and_b32_e32 v45, 0xfff, v49
	v_cmp_ne_u32_e32 vcc, 0, v45
	s_nop 1
	v_cndmask_b32_e64 v151, 0, -1, vcc
	v_add_u32_e32 v45, v49, v151
	v_mad_i64_i32 v[46:47], s[14:15], v45, s79, v[32:33]
	global_load_ushort v133, v[46:47], off
	v_add_u32_e32 v49, 8, v42
	v_mad_i64_i32 v[46:47], s[14:15], v49, s79, v[32:33]
	global_load_ushort v134, v[46:47], off
	v_and_b32_e32 v45, 0xfff, v49
	v_cmp_ne_u32_e32 vcc, 0, v45
	s_nop 1
	v_cndmask_b32_e64 v152, 0, -1, vcc
	v_add_u32_e32 v45, v49, v152
	v_mad_i64_i32 v[46:47], s[14:15], v45, s79, v[32:33]
	global_load_ushort v135, v[46:47], off
	v_add_u32_e32 v49, 12, v42
	v_mad_i64_i32 v[46:47], s[14:15], v49, s79, v[32:33]
	global_load_ushort v136, v[46:47], off
	v_and_b32_e32 v45, 0xfff, v49
	v_cmp_ne_u32_e32 vcc, 0, v45
	s_nop 1
	v_cndmask_b32_e64 v153, 0, -1, vcc
	v_add_u32_e32 v45, v49, v153
	v_mad_i64_i32 v[46:47], s[14:15], v45, s79, v[32:33]
	global_load_ushort v137, v[46:47], off
	v_add_u32_e32 v49, 16, v42
	v_mad_i64_i32 v[46:47], s[14:15], v49, s79, v[32:33]
	global_load_ushort v138, v[46:47], off
	v_and_b32_e32 v45, 0xfff, v49
	v_cmp_ne_u32_e32 vcc, 0, v45
	s_nop 1
	v_cndmask_b32_e64 v154, 0, -1, vcc
	v_add_u32_e32 v45, v49, v154
	v_mad_i64_i32 v[46:47], s[14:15], v45, s79, v[32:33]
	global_load_ushort v139, v[46:47], off
	v_add_u32_e32 v49, 20, v42
	v_mad_i64_i32 v[46:47], s[14:15], v49, s79, v[32:33]
	global_load_ushort v140, v[46:47], off
	v_and_b32_e32 v45, 0xfff, v49
	v_cmp_ne_u32_e32 vcc, 0, v45
	s_nop 1
	v_cndmask_b32_e64 v155, 0, -1, vcc
	v_add_u32_e32 v45, v49, v155
	v_mad_i64_i32 v[46:47], s[14:15], v45, s79, v[32:33]
	global_load_ushort v141, v[46:47], off
	v_add_u32_e32 v49, 24, v42
	v_mad_i64_i32 v[46:47], s[14:15], v49, s79, v[32:33]
	global_load_ushort v142, v[46:47], off
	v_and_b32_e32 v45, 0xfff, v49
	v_cmp_ne_u32_e32 vcc, 0, v45
	s_nop 1
	v_cndmask_b32_e64 v156, 0, -1, vcc
	v_add_u32_e32 v45, v49, v156
	v_mad_i64_i32 v[46:47], s[14:15], v45, s79, v[32:33]
	global_load_ushort v143, v[46:47], off
	v_add_u32_e32 v49, 28, v42
	v_mad_i64_i32 v[46:47], s[14:15], v49, s79, v[32:33]
	global_load_ushort v144, v[46:47], off
	v_and_b32_e32 v45, 0xfff, v49
	v_cmp_ne_u32_e32 vcc, 0, v45
	s_nop 1
	v_cndmask_b32_e64 v157, 0, -1, vcc
	v_add_u32_e32 v45, v49, v157
	v_mad_i64_i32 v[46:47], s[14:15], v45, s79, v[32:33]
	global_load_ushort v145, v[46:47], off
	s_waitcnt vmcnt(14)
	v_lshlrev_b32_e32 v43, 16, v130
	v_lshlrev_b32_e32 v45, 16, v131
	v_and_b32_e32 v45, v45, v150
	v_sub_f32_e32 v44, v45, v43
	v_fmac_f32_e32 v43, v40, v44
	s_and_saveexec_b64 s[14:15], s[10:11]
	s_xor_b64 s[14:15], exec, s[14:15]
	s_cbranch_execz .Lprep_1071_0
	s_and_saveexec_b64 s[16:17], s[12:13]
	s_cbranch_execz .Lprep_1070_0
	v_mul_f32_e32 v43, 0xbfb8aa3b, v43
	v_exp_f32_e32 v43, v43
	s_nop 0
	v_add_f32_e32 v43, 1.0, v43
	v_div_scale_f32 v44, s[20:21], v43, v43, 1.0
	v_rcp_f32_e32 v45, v44
	v_div_scale_f32 v46, vcc, 1.0, v43, 1.0
	v_fma_f32 v47, -v44, v45, 1.0
	v_fmac_f32_e32 v45, v47, v45
	v_mul_f32_e32 v47, v46, v45
	v_fma_f32 v48, -v44, v47, v46
	v_fmac_f32_e32 v47, v48, v45
	v_fma_f32 v44, -v44, v47, v46
	v_div_fmas_f32 v44, v44, v45, v47
	v_div_fixup_f32 v43, v44, v43, 1.0

; DI float bf2f(u16 h) { return __uint_as_float(((unsigned)h) << 16); }
; DI float sigmoidf_(float x) { return 1.f / (1.f + __expf(-x)); }
; DI void phase_prep(const PRef& p, int l) {
;     ...
;       float pv = bf2f(rw[(size_t)tok * 896 + col]);
;       float pp = ((tok & (SEQ - 1)) != 0) ? bf2f(rw[(size_t)(tok - 1) * 896 + col]) : 0.f;
;       float ps = pv + (pp - pv) * mu[col];
;       float a = (j < 32) ? tanhf(ps) : (j < 64) ? ps : sigmoidf_(ps);
;       act[i * 128 + j] = a;
.Lprep_1074_0:
	s_andn2_saveexec_b64 s[16:17], s[16:17]
	s_cbranch_execz .Lprep_1063_0
	v_mul_f32_e32 v44, v43, v43
	v_fmamk_f32 v45, v44, 0xbbbac73d, v238
	v_fmaak_f32 v45, v44, v45, 0xbd5c1c4e
	v_fmaak_f32 v45, v44, v45, 0x3e088382
	v_fmaak_f32 v45, v44, v45, 0xbeaaaa99
	v_mul_f32_e64 v45, |v43|, v45
	v_fma_f32 v44, v44, v45, |v43|
.Lprep_1063_0:
	s_or_b64 exec, exec, s[16:17]
	v_bfi_b32 v43, s75, v44, v43
.Lprep_1064_0:
	s_or_b64 exec, exec, s[14:15]
	ds_write_b32 v41, v43
	v_add_u32_e32 v41, 0x800, v41
	s_waitcnt vmcnt(12)
	v_lshlrev_b32_e32 v43, 16, v132
	v_lshlrev_b32_e32 v45, 16, v133
	v_and_b32_e32 v45, v45, v151
	v_sub_f32_e32 v44, v45, v43
	v_fmac_f32_e32 v43, v40, v44
	s_and_saveexec_b64 s[14:15], s[10:11]
	s_xor_b64 s[14:15], exec, s[14:15]
	s_cbranch_execz .Lprep_1071_1
	s_and_saveexec_b64 s[16:17], s[12:13]
	s_cbranch_execz .Lprep_1070_1
	v_mul_f32_e32 v43, 0xbfb8aa3b, v43
	v_exp_f32_e32 v43, v43
	s_nop 0
	v_add_f32_e32 v43, 1.0, v43
	v_div_scale_f32 v44, s[20:21], v43, v43, 1.0
	v_rcp_f32_e32 v45, v44
	v_div_scale_f32 v46, vcc, 1.0, v43, 1.0
	v_fma_f32 v47, -v44, v45, 1.0
	v_fmac_f32_e32 v45, v47, v45
	v_mul_f32_e32 v47, v46, v45
	v_fma_f32 v48, -v44, v47, v46
	v_fmac_f32_e32 v47, v48, v45
	v_fma_f32 v44, -v44, v47, v46
	v_div_fmas_f32 v44, v44, v45, v47
	v_div_fixup_f32 v43, v44, v43, 1.0

; DI float bf2f(u16 h) { return __uint_as_float(((unsigned)h) << 16); }
; DI float sigmoidf_(float x) { return 1.f / (1.f + __expf(-x)); }
; DI void phase_prep(const PRef& p, int l) {
;     ...
;       float pv = bf2f(rw[(size_t)tok * 896 + col]);
;       float pp = ((tok & (SEQ - 1)) != 0) ? bf2f(rw[(size_t)(tok - 1) * 896 + col]) : 0.f;
;       float ps = pv + (pp - pv) * mu[col];
;       float a = (j < 32) ? tanhf(ps) : (j < 64) ? ps : sigmoidf_(ps);
;       act[i * 128 + j] = a;
.Lprep_1074_1:
	s_andn2_saveexec_b64 s[16:17], s[16:17]
	s_cbranch_execz .Lprep_1063_1
	v_mul_f32_e32 v44, v43, v43
	v_fmamk_f32 v45, v44, 0xbbbac73d, v238
	v_fmaak_f32 v45, v44, v45, 0xbd5c1c4e
	v_fmaak_f32 v45, v44, v45, 0x3e088382
	v_fmaak_f32 v45, v44, v45, 0xbeaaaa99
	v_mul_f32_e64 v45, |v43|, v45
	v_fma_f32 v44, v44, v45, |v43|
.Lprep_1063_1:
	s_or_b64 exec, exec, s[16:17]
	v_bfi_b32 v43, s75, v44, v43
.Lprep_1064_1:
	s_or_b64 exec, exec, s[14:15]
	ds_write_b32 v41, v43
	v_add_u32_e32 v41, 0x800, v41
	s_waitcnt vmcnt(10)
	v_lshlrev_b32_e32 v43, 16, v134
	v_lshlrev_b32_e32 v45, 16, v135
	v_and_b32_e32 v45, v45, v152
	v_sub_f32_e32 v44, v45, v43
	v_fmac_f32_e32 v43, v40, v44
	s_and_saveexec_b64 s[14:15], s[10:11]
	s_xor_b64 s[14:15], exec, s[14:15]
	s_cbranch_execz .Lprep_1071_2
	s_and_saveexec_b64 s[16:17], s[12:13]
	s_cbranch_execz .Lprep_1070_2
	v_mul_f32_e32 v43, 0xbfb8aa3b, v43
	v_exp_f32_e32 v43, v43
	s_nop 0
	v_add_f32_e32 v43, 1.0, v43
	v_div_scale_f32 v44, s[20:21], v43, v43, 1.0
	v_rcp_f32_e32 v45, v44
	v_div_scale_f32 v46, vcc, 1.0, v43, 1.0
	v_fma_f32 v47, -v44, v45, 1.0
	v_fmac_f32_e32 v45, v47, v45
	v_mul_f32_e32 v47, v46, v45
	v_fma_f32 v48, -v44, v47, v46
	v_fmac_f32_e32 v47, v48, v45
	v_fma_f32 v44, -v44, v47, v46
	v_div_fmas_f32 v44, v44, v45, v47
	v_div_fixup_f32 v43, v44, v43, 1.0

; DI float bf2f(u16 h) { return __uint_as_float(((unsigned)h) << 16); }
; DI float sigmoidf_(float x) { return 1.f / (1.f + __expf(-x)); }
; DI void phase_prep(const PRef& p, int l) {
;     ...
;       float pv = bf2f(rw[(size_t)tok * 896 + col]);
;       float pp = ((tok & (SEQ - 1)) != 0) ? bf2f(rw[(size_t)(tok - 1) * 896 + col]) : 0.f;
;       float ps = pv + (pp - pv) * mu[col];
;       float a = (j < 32) ? tanhf(ps) : (j < 64) ? ps : sigmoidf_(ps);
;       act[i * 128 + j] = a;
.Lprep_1074_2:
	s_andn2_saveexec_b64 s[16:17], s[16:17]
	s_cbranch_execz .Lprep_1063_2
	v_mul_f32_e32 v44, v43, v43
	v_fmamk_f32 v45, v44, 0xbbbac73d, v238
	v_fmaak_f32 v45, v44, v45, 0xbd5c1c4e
	v_fmaak_f32 v45, v44, v45, 0x3e088382
	v_fmaak_f32 v45, v44, v45, 0xbeaaaa99
	v_mul_f32_e64 v45, |v43|, v45
	v_fma_f32 v44, v44, v45, |v43|
.Lprep_1063_2:
	s_or_b64 exec, exec, s[16:17]
	v_bfi_b32 v43, s75, v44, v43
.Lprep_1064_2:
	s_or_b64 exec, exec, s[14:15]
	ds_write_b32 v41, v43
	v_add_u32_e32 v41, 0x800, v41
	s_waitcnt vmcnt(8)
	v_lshlrev_b32_e32 v43, 16, v136
	v_lshlrev_b32_e32 v45, 16, v137
	v_and_b32_e32 v45, v45, v153
	v_sub_f32_e32 v44, v45, v43
	v_fmac_f32_e32 v43, v40, v44
	s_and_saveexec_b64 s[14:15], s[10:11]
	s_xor_b64 s[14:15], exec, s[14:15]
	s_cbranch_execz .Lprep_1071_3
	s_and_saveexec_b64 s[16:17], s[12:13]
	s_cbranch_execz .Lprep_1070_3
	v_mul_f32_e32 v43, 0xbfb8aa3b, v43
	v_exp_f32_e32 v43, v43
	s_nop 0
	v_add_f32_e32 v43, 1.0, v43
	v_div_scale_f32 v44, s[20:21], v43, v43, 1.0
	v_rcp_f32_e32 v45, v44
	v_div_scale_f32 v46, vcc, 1.0, v43, 1.0
	v_fma_f32 v47, -v44, v45, 1.0
	v_fmac_f32_e32 v45, v47, v45
	v_mul_f32_e32 v47, v46, v45
	v_fma_f32 v48, -v44, v47, v46
	v_fmac_f32_e32 v47, v48, v45
	v_fma_f32 v44, -v44, v47, v46
	v_div_fmas_f32 v44, v44, v45, v47
	v_div_fixup_f32 v43, v44, v43, 1.0

; DI float bf2f(u16 h) { return __uint_as_float(((unsigned)h) << 16); }
; DI float sigmoidf_(float x) { return 1.f / (1.f + __expf(-x)); }
; DI void phase_prep(const PRef& p, int l) {
;     ...
;       float pv = bf2f(rw[(size_t)tok * 896 + col]);
;       float pp = ((tok & (SEQ - 1)) != 0) ? bf2f(rw[(size_t)(tok - 1) * 896 + col]) : 0.f;
;       float ps = pv + (pp - pv) * mu[col];
;       float a = (j < 32) ? tanhf(ps) : (j < 64) ? ps : sigmoidf_(ps);
;       act[i * 128 + j] = a;
.Lprep_1074_3:
	s_andn2_saveexec_b64 s[16:17], s[16:17]
	s_cbranch_execz .Lprep_1063_3
	v_mul_f32_e32 v44, v43, v43
	v_fmamk_f32 v45, v44, 0xbbbac73d, v238
	v_fmaak_f32 v45, v44, v45, 0xbd5c1c4e
	v_fmaak_f32 v45, v44, v45, 0x3e088382
	v_fmaak_f32 v45, v44, v45, 0xbeaaaa99
	v_mul_f32_e64 v45, |v43|, v45
	v_fma_f32 v44, v44, v45, |v43|
.Lprep_1063_3:
	s_or_b64 exec, exec, s[16:17]
	v_bfi_b32 v43, s75, v44, v43
.Lprep_1064_3:
	s_or_b64 exec, exec, s[14:15]
	ds_write_b32 v41, v43
	v_add_u32_e32 v41, 0x800, v41
	s_waitcnt vmcnt(6)
	v_lshlrev_b32_e32 v43, 16, v138
	v_lshlrev_b32_e32 v45, 16, v139
	v_and_b32_e32 v45, v45, v154
	v_sub_f32_e32 v44, v45, v43
	v_fmac_f32_e32 v43, v40, v44
	s_and_saveexec_b64 s[14:15], s[10:11]
	s_xor_b64 s[14:15], exec, s[14:15]
	s_cbranch_execz .Lprep_1071_4
	s_and_saveexec_b64 s[16:17], s[12:13]
	s_cbranch_execz .Lprep_1070_4
	v_mul_f32_e32 v43, 0xbfb8aa3b, v43
	v_exp_f32_e32 v43, v43
	s_nop 0
	v_add_f32_e32 v43, 1.0, v43
	v_div_scale_f32 v44, s[20:21], v43, v43, 1.0
	v_rcp_f32_e32 v45, v44
	v_div_scale_f32 v46, vcc, 1.0, v43, 1.0
	v_fma_f32 v47, -v44, v45, 1.0
	v_fmac_f32_e32 v45, v47, v45
	v_mul_f32_e32 v47, v46, v45
	v_fma_f32 v48, -v44, v47, v46
	v_fmac_f32_e32 v47, v48, v45
	v_fma_f32 v44, -v44, v47, v46
	v_div_fmas_f32 v44, v44, v45, v47
	v_div_fixup_f32 v43, v44, v43, 1.0

; DI float bf2f(u16 h) { return __uint_as_float(((unsigned)h) << 16); }
; DI float sigmoidf_(float x) { return 1.f / (1.f + __expf(-x)); }
; DI void phase_prep(const PRef& p, int l) {
;     ...
;       float pv = bf2f(rw[(size_t)tok * 896 + col]);
;       float pp = ((tok & (SEQ - 1)) != 0) ? bf2f(rw[(size_t)(tok - 1) * 896 + col]) : 0.f;
;       float ps = pv + (pp - pv) * mu[col];
;       float a = (j < 32) ? tanhf(ps) : (j < 64) ? ps : sigmoidf_(ps);
;       act[i * 128 + j] = a;
.Lprep_1074_4:
	s_andn2_saveexec_b64 s[16:17], s[16:17]
	s_cbranch_execz .Lprep_1063_4
	v_mul_f32_e32 v44, v43, v43
	v_fmamk_f32 v45, v44, 0xbbbac73d, v238
	v_fmaak_f32 v45, v44, v45, 0xbd5c1c4e
	v_fmaak_f32 v45, v44, v45, 0x3e088382
	v_fmaak_f32 v45, v44, v45, 0xbeaaaa99
	v_mul_f32_e64 v45, |v43|, v45
	v_fma_f32 v44, v44, v45, |v43|
.Lprep_1063_4:
	s_or_b64 exec, exec, s[16:17]
	v_bfi_b32 v43, s75, v44, v43
.Lprep_1064_4:
	s_or_b64 exec, exec, s[14:15]
	ds_write_b32 v41, v43
	v_add_u32_e32 v41, 0x800, v41
	s_waitcnt vmcnt(4)
	v_lshlrev_b32_e32 v43, 16, v140
	v_lshlrev_b32_e32 v45, 16, v141
	v_and_b32_e32 v45, v45, v155
	v_sub_f32_e32 v44, v45, v43
	v_fmac_f32_e32 v43, v40, v44
	s_and_saveexec_b64 s[14:15], s[10:11]
	s_xor_b64 s[14:15], exec, s[14:15]
	s_cbranch_execz .Lprep_1071_5
	s_and_saveexec_b64 s[16:17], s[12:13]
	s_cbranch_execz .Lprep_1070_5
	v_mul_f32_e32 v43, 0xbfb8aa3b, v43
	v_exp_f32_e32 v43, v43
	s_nop 0
	v_add_f32_e32 v43, 1.0, v43
	v_div_scale_f32 v44, s[20:21], v43, v43, 1.0
	v_rcp_f32_e32 v45, v44
	v_div_scale_f32 v46, vcc, 1.0, v43, 1.0
	v_fma_f32 v47, -v44, v45, 1.0
	v_fmac_f32_e32 v45, v47, v45
	v_mul_f32_e32 v47, v46, v45
	v_fma_f32 v48, -v44, v47, v46
	v_fmac_f32_e32 v47, v48, v45
	v_fma_f32 v44, -v44, v47, v46
	v_div_fmas_f32 v44, v44, v45, v47
	v_div_fixup_f32 v43, v44, v43, 1.0

; DI float bf2f(u16 h) { return __uint_as_float(((unsigned)h) << 16); }
; DI float sigmoidf_(float x) { return 1.f / (1.f + __expf(-x)); }
; DI void phase_prep(const PRef& p, int l) {
;     ...
;       float pv = bf2f(rw[(size_t)tok * 896 + col]);
;       float pp = ((tok & (SEQ - 1)) != 0) ? bf2f(rw[(size_t)(tok - 1) * 896 + col]) : 0.f;
;       float ps = pv + (pp - pv) * mu[col];
;       float a = (j < 32) ? tanhf(ps) : (j < 64) ? ps : sigmoidf_(ps);
;       act[i * 128 + j] = a;
.Lprep_1074_5:
	s_andn2_saveexec_b64 s[16:17], s[16:17]
	s_cbranch_execz .Lprep_1063_5
	v_mul_f32_e32 v44, v43, v43
	v_fmamk_f32 v45, v44, 0xbbbac73d, v238
	v_fmaak_f32 v45, v44, v45, 0xbd5c1c4e
	v_fmaak_f32 v45, v44, v45, 0x3e088382
	v_fmaak_f32 v45, v44, v45, 0xbeaaaa99
	v_mul_f32_e64 v45, |v43|, v45
	v_fma_f32 v44, v44, v45, |v43|
.Lprep_1063_5:
	s_or_b64 exec, exec, s[16:17]
	v_bfi_b32 v43, s75, v44, v43
.Lprep_1064_5:
	s_or_b64 exec, exec, s[14:15]
	ds_write_b32 v41, v43
	v_add_u32_e32 v41, 0x800, v41
	s_waitcnt vmcnt(2)
	v_lshlrev_b32_e32 v43, 16, v142
	v_lshlrev_b32_e32 v45, 16, v143
	v_and_b32_e32 v45, v45, v156
	v_sub_f32_e32 v44, v45, v43
	v_fmac_f32_e32 v43, v40, v44
	s_and_saveexec_b64 s[14:15], s[10:11]
	s_xor_b64 s[14:15], exec, s[14:15]
	s_cbranch_execz .Lprep_1071_6
	s_and_saveexec_b64 s[16:17], s[12:13]
	s_cbranch_execz .Lprep_1070_6
	v_mul_f32_e32 v43, 0xbfb8aa3b, v43
	v_exp_f32_e32 v43, v43
	s_nop 0
	v_add_f32_e32 v43, 1.0, v43
	v_div_scale_f32 v44, s[20:21], v43, v43, 1.0
	v_rcp_f32_e32 v45, v44
	v_div_scale_f32 v46, vcc, 1.0, v43, 1.0
	v_fma_f32 v47, -v44, v45, 1.0
	v_fmac_f32_e32 v45, v47, v45
	v_mul_f32_e32 v47, v46, v45
	v_fma_f32 v48, -v44, v47, v46
	v_fmac_f32_e32 v47, v48, v45
	v_fma_f32 v44, -v44, v47, v46
	v_div_fmas_f32 v44, v44, v45, v47
	v_div_fixup_f32 v43, v44, v43, 1.0

; DI float bf2f(u16 h) { return __uint_as_float(((unsigned)h) << 16); }
; DI float sigmoidf_(float x) { return 1.f / (1.f + __expf(-x)); }
; DI void phase_prep(const PRef& p, int l) {
;     ...
;       float pv = bf2f(rw[(size_t)tok * 896 + col]);
;       float pp = ((tok & (SEQ - 1)) != 0) ? bf2f(rw[(size_t)(tok - 1) * 896 + col]) : 0.f;
;       float ps = pv + (pp - pv) * mu[col];
;       float a = (j < 32) ? tanhf(ps) : (j < 64) ? ps : sigmoidf_(ps);
;       act[i * 128 + j] = a;
.Lprep_1074_6:
	s_andn2_saveexec_b64 s[16:17], s[16:17]
	s_cbranch_execz .Lprep_1063_6
	v_mul_f32_e32 v44, v43, v43
	v_fmamk_f32 v45, v44, 0xbbbac73d, v238
	v_fmaak_f32 v45, v44, v45, 0xbd5c1c4e
	v_fmaak_f32 v45, v44, v45, 0x3e088382
	v_fmaak_f32 v45, v44, v45, 0xbeaaaa99
	v_mul_f32_e64 v45, |v43|, v45
	v_fma_f32 v44, v44, v45, |v43|
.Lprep_1063_6:
	s_or_b64 exec, exec, s[16:17]
	v_bfi_b32 v43, s75, v44, v43
.Lprep_1064_6:
	s_or_b64 exec, exec, s[14:15]
	ds_write_b32 v41, v43
	v_add_u32_e32 v41, 0x800, v41
	s_waitcnt vmcnt(0)
	v_lshlrev_b32_e32 v43, 16, v144
	v_lshlrev_b32_e32 v45, 16, v145
	v_and_b32_e32 v45, v45, v157
	v_sub_f32_e32 v44, v45, v43
	v_fmac_f32_e32 v43, v40, v44
	s_and_saveexec_b64 s[14:15], s[10:11]
	s_xor_b64 s[14:15], exec, s[14:15]
	s_cbranch_execz .Lprep_1071_7
	s_and_saveexec_b64 s[16:17], s[12:13]
	s_cbranch_execz .Lprep_1070_7
	v_mul_f32_e32 v43, 0xbfb8aa3b, v43
	v_exp_f32_e32 v43, v43
	s_nop 0
	v_add_f32_e32 v43, 1.0, v43
	v_div_scale_f32 v44, s[20:21], v43, v43, 1.0
	v_rcp_f32_e32 v45, v44
	v_div_scale_f32 v46, vcc, 1.0, v43, 1.0
	v_fma_f32 v47, -v44, v45, 1.0
	v_fmac_f32_e32 v45, v47, v45
	v_mul_f32_e32 v47, v46, v45
	v_fma_f32 v48, -v44, v47, v46
	v_fmac_f32_e32 v47, v48, v45
	v_fma_f32 v44, -v44, v47, v46
	v_div_fmas_f32 v44, v44, v45, v47
	v_div_fixup_f32 v43, v44, v43, 1.0

; DI float sigmoidf_(float x) { return 1.f / (1.f + __expf(-x)); }
; DI void phase_prep(const PRef& p, int l) {
;     ...
;       float a = (j < 32) ? tanhf(ps) : (j < 64) ? ps : sigmoidf_(ps);
;       act[i * 128 + j] = a;
.Lprep_1074_7:
	s_andn2_saveexec_b64 s[16:17], s[16:17]
	s_cbranch_execz .Lprep_1063_7
	v_mul_f32_e32 v44, v43, v43
	v_fmamk_f32 v45, v44, 0xbbbac73d, v238
	v_fmaak_f32 v45, v44, v45, 0xbd5c1c4e
	v_fmaak_f32 v45, v44, v45, 0x3e088382
	v_fmaak_f32 v45, v44, v45, 0xbeaaaa99
	v_mul_f32_e64 v45, |v43|, v45
	v_fma_f32 v44, v44, v45, |v43|
.Lprep_1063_7:
	s_or_b64 exec, exec, s[16:17]
	v_bfi_b32 v43, s75, v44, v43
.Lprep_1064_7:
	s_or_b64 exec, exec, s[14:15]
	ds_write_b32 v41, v43
